# out-proj epilogue: second-half residual loads hoisted (no load waits behind the stores) + sc1 on its HB stores (consumed by the gate-up phase on other XCDs), on top of the best cache-policy version
# baseline (speedup 1.0000x reference)
; __device__ __forceinline__ unsigned cvt_pk(float lo, float hi) { unsigned r; asm("v_cvt_pk_bf16_f32 %0, %1, %2" : "=v"(r) : "v"(lo), "v"(hi)); return r; }
;     __device__ __forceinline__ void operator()(AccRef acc, const pg8::Unit& u, int wr, int wc, int, int) const {
;     ...
;                 v4u pw[4][2];
; #pragma unroll
;                 for (int m = 0; m < 4; ++m) { const int row = u.pm * 256 + ai * 128 + wr * 64 + m * 16 + fr;
; #pragma unroll
;                     for (int bj = 0; bj < 2; ++bj) pw[m][bj] = *(const v4u*)(RB + (size_t)row * DM + u.pn * 256 + bj * 128 + wc * 32 + 8 * fq); }
; #pragma unroll
;                 for (int m = 0; m < 4; ++m)
; #pragma unroll
;                     for (int bj = 0; bj < 2; ++bj) { const v4u w = pw[m][bj]; r0[m][bj] = (f32x4){bf_lo(w.x), bf_hi(w.x), bf_lo(w.y), bf_hi(w.y)}; r1[m][bj] = (f32x4){bf_lo(w.z), bf_hi(w.z), bf_lo(w.w), bf_hi(w.w)}; }
;             }
;             asm volatile("" ::: "memory");
; #pragma unroll
;             for (int m = 0; m < 4; ++m) {
;                 const int row = u.pm * 256 + ai * 128 + wr * 64 + m * 16 + fr;
;                 float ss = 0.f;
; #pragma unroll
;                 for (int bj = 0; bj < 2; ++bj) {
;                     const int c0 = u.pn * 256 + bj * 128 + wc * 32 + 8 * fq;
;                     const f32x4 o0 = r0[m][bj] + acc[ai][bj][m][0], o1 = r1[m][bj] + acc[ai][bj][m][1];
;                     v4u w; w.x = cvt_pk(o0[0], o0[1]); w.y = cvt_pk(o0[2], o0[3]); w.z = cvt_pk(o1[0], o1[1]); w.w = cvt_pk(o1[2], o1[3]);
;                     *(v4u*)(HB + (size_t)row * DM + c0) = w;
;                     ss += (o0[0] * o0[0] + o0[1] * o0[1]) + (o0[2] * o0[2] + o0[3] * o0[3]) + (o1[0] * o1[0] + o1[1] * o1[1]) + (o1[2] * o1[2] + o1[3] * o1[3]);
;                 }
;                 if (ssq_off >= 0) { ss += __shfl_xor(ss, 16); ss += __shfl_xor(ss, 32); if (fq == 0) __hip_atomic_fetch_add(ssq + row, ss, __ATOMIC_RELAXED, __HIP_MEMORY_SCOPE_AGENT); }
.LBB0_459:
	s_mov_b64 s[36:37], s[44:45]
	s_mov_b64 s[38:39], s[46:47]
	s_add_u32 s58, s36, 0x7800000
	s_addc_u32 s59, s37, 0
	s_add_u32 s56, s36, 0x22000
	v_mov_b32_e32 v130, v196
	s_addc_u32 s57, s37, 0
	s_lshl_b32 s15, s76, 8
	s_lshl_b32 s38, s66, 8
	s_add_i32 s15, s15, s35
	v_ashrrev_i32_e32 v128, 1, v130
	s_ashr_i32 s39, s38, 31
	v_and_or_b32 v166, v130, 15, s15
	v_and_b32_e32 v128, -8, v128
	s_or_b32 s15, s38, s28
	s_lshl_b64 s[38:39], s[38:39], 1
	v_add_u32_e32 v164, s15, v128
	s_add_u32 s15, s36, s38
	s_addc_u32 s31, s37, s39
	s_add_u32 s36, s15, s70
	s_addc_u32 s37, s31, 0
	v_ashrrev_i32_e32 v129, 31, v128
	v_lshl_add_u64 v[128:129], v[128:129], 1, s[36:37]
	s_mov_b64 s[36:37], 0x3600000
	v_ashrrev_i32_e32 v167, 31, v166
	v_lshl_add_u64 v[168:169], v[128:129], 0, s[36:37]
	v_lshlrev_b64 v[200:201], 11, v[166:167]
	v_lshl_add_u64 v[128:129], v[168:169], 0, v[200:201]
	s_mov_b64 s[78:79], 0x40000
	v_lshl_add_u64 v[244:245], v[128:129], 0, s[78:79]
	global_load_dwordx4 v[188:191], v[128:129], off
	global_load_dwordx4 v[192:195], v[128:129], off offset:256
	global_load_dwordx4 v[212:215], v[244:245], off
	global_load_dwordx4 v[216:219], v[244:245], off offset:256
	v_or_b32_e32 v176, 16, v166
	v_ashrrev_i32_e32 v177, 31, v176
	v_or_b32_e32 v172, 32, v166
	v_lshlrev_b64 v[180:181], 11, v[176:177]
	v_ashrrev_i32_e32 v173, 31, v172
	v_or_b32_e32 v170, 48, v166
	v_lshl_add_u64 v[128:129], v[168:169], 0, v[180:181]
	v_lshlrev_b64 v[178:179], 11, v[172:173]
	v_ashrrev_i32_e32 v171, 31, v170
	v_lshl_add_u64 v[244:245], v[128:129], 0, s[78:79]
	global_load_dwordx4 v[148:151], v[128:129], off
	global_load_dwordx4 v[144:147], v[128:129], off offset:256
	global_load_dwordx4 v[220:223], v[244:245], off
	global_load_dwordx4 v[224:227], v[244:245], off offset:256
	v_lshl_add_u64 v[128:129], v[168:169], 0, v[178:179]
	v_lshlrev_b64 v[174:175], 11, v[170:171]
	v_lshl_add_u64 v[244:245], v[128:129], 0, s[78:79]
	global_load_dwordx4 v[140:143], v[128:129], off
	global_load_dwordx4 v[136:139], v[128:129], off offset:256
	global_load_dwordx4 v[228:231], v[244:245], off
	global_load_dwordx4 v[232:235], v[244:245], off offset:256
	v_lshl_add_u64 v[128:129], v[168:169], 0, v[174:175]
	v_cmp_gt_u32_e32 vcc, 16, v130
	v_lshl_add_u64 v[244:245], v[128:129], 0, s[78:79]
	global_load_dwordx4 v[132:135], v[128:129], off
	s_nop 0
	global_load_dwordx4 v[128:131], v[128:129], off offset:256
	global_load_dwordx4 v[236:239], v[244:245], off
	global_load_dwordx4 v[240:243], v[244:245], off offset:256
	v_ashrrev_i32_e32 v165, 31, v164
	v_lshl_add_u64 v[200:201], s[58:59], 0, v[200:201]
	v_lshl_add_u64 v[200:201], v[164:165], 1, v[200:201]
	s_waitcnt vmcnt(0)
	v_lshlrev_b32_e32 v202, 16, v188
	v_and_b32_e32 v203, 0xffff0000, v188
	v_lshlrev_b32_e32 v188, 16, v189
	v_and_b32_e32 v189, 0xffff0000, v189
	v_lshlrev_b32_e32 v204, 16, v190
	v_and_b32_e32 v205, 0xffff0000, v190
	v_lshlrev_b32_e32 v190, 16, v191
	v_and_b32_e32 v191, 0xffff0000, v191
	v_lshlrev_b32_e32 v206, 16, v192
	v_and_b32_e32 v207, 0xffff0000, v192
	v_lshlrev_b32_e32 v192, 16, v193
	v_and_b32_e32 v193, 0xffff0000, v193
	v_lshlrev_b32_e32 v208, 16, v194
	v_and_b32_e32 v209, 0xffff0000, v194
	v_lshlrev_b32_e32 v194, 16, v195
	v_and_b32_e32 v195, 0xffff0000, v195
	v_pk_add_f32 v[126:127], v[126:127], v[188:189]
	v_pk_add_f32 v[124:125], v[124:125], v[202:203]
	v_pk_add_f32 v[188:189], v[122:123], v[190:191]
	v_pk_add_f32 v[190:191], v[120:121], v[204:205]
	v_cvt_pk_bf16_f32 v120, v124, v125
	v_cvt_pk_bf16_f32 v121, v126, v127
	v_cvt_pk_bf16_f32 v123, v188, v189
	v_pk_add_f32 v[118:119], v[118:119], v[192:193]
	v_cvt_pk_bf16_f32 v122, v190, v191
	global_store_dwordx4 v[200:201], v[120:123], off sc1
	v_pk_add_f32 v[116:117], v[116:117], v[206:207]
	s_nop 0
	v_pk_add_f32 v[120:121], v[114:115], v[194:195]
	v_pk_add_f32 v[122:123], v[112:113], v[208:209]
	v_cvt_pk_bf16_f32 v113, v118, v119
	v_cvt_pk_bf16_f32 v112, v116, v117
	v_cvt_pk_bf16_f32 v115, v120, v121
	s_nop 0
	v_cvt_pk_bf16_f32 v114, v122, v123
	global_store_dwordx4 v[200:201], v[112:115], off offset:256 sc1
	s_nop 1
	v_mul_f32_e32 v113, v125, v125
	v_mul_f32_e32 v114, v127, v127
	v_fmac_f32_e32 v113, v124, v124
	v_fmac_f32_e32 v114, v126, v126
	v_add_f32_e32 v113, v113, v114
	v_mul_f32_e32 v114, v191, v191
	v_fmac_f32_e32 v114, v190, v190
	v_add_f32_e32 v113, v114, v113
	v_mul_f32_e32 v114, v117, v117
	v_mul_f32_e32 v115, v119, v119
	v_mul_f32_e32 v112, v189, v189
	v_fmac_f32_e32 v114, v116, v116
	v_fmac_f32_e32 v115, v118, v118
	v_fmac_f32_e32 v112, v188, v188
	v_add_f32_e32 v114, v114, v115
	v_mul_f32_e32 v115, v123, v123
	v_add_f32_e32 v112, v112, v113
	v_mul_f32_e32 v113, v121, v121
	v_fmac_f32_e32 v115, v122, v122
	v_fmac_f32_e32 v113, v120, v120
	v_add_f32_e32 v114, v115, v114
	v_add_f32_e32 v113, v113, v114
	v_add_f32_e32 v112, v112, v113
	ds_bpermute_b32 v113, v197, v112
	s_waitcnt lgkmcnt(0)
	v_add_f32_e32 v112, v112, v113
	ds_bpermute_b32 v113, v198, v112
	s_and_saveexec_b64 s[66:67], vcc
	s_cbranch_execz .LBB0_461
	s_waitcnt lgkmcnt(0)
	v_add_f32_e32 v114, v112, v113
	v_lshl_add_u64 v[112:113], v[166:167], 2, s[56:57]
	global_atomic_add_f32 v[112:113], v114, off
; __device__ __forceinline__ unsigned cvt_pk(float lo, float hi) { unsigned r; asm("v_cvt_pk_bf16_f32 %0, %1, %2" : "=v"(r) : "v"(lo), "v"(hi)); return r; }
;     __device__ __forceinline__ void operator()(AccRef acc, const pg8::Unit& u, int wr, int wc, int, int) const {
;     ...
;             for (int m = 0; m < 4; ++m) {
;                 const int row = u.pm * 256 + ai * 128 + wr * 64 + m * 16 + fr;
;                 float ss = 0.f;
; #pragma unroll
;                 for (int bj = 0; bj < 2; ++bj) {
;                     const int c0 = u.pn * 256 + bj * 128 + wc * 32 + 8 * fq;
;                     const f32x4 o0 = r0[m][bj] + acc[ai][bj][m][0], o1 = r1[m][bj] + acc[ai][bj][m][1];
;                     v4u w; w.x = cvt_pk(o0[0], o0[1]); w.y = cvt_pk(o0[2], o0[3]); w.z = cvt_pk(o1[0], o1[1]); w.w = cvt_pk(o1[2], o1[3]);
;                     *(v4u*)(HB + (size_t)row * DM + c0) = w;
;                     ss += (o0[0] * o0[0] + o0[1] * o0[1]) + (o0[2] * o0[2] + o0[3] * o0[3]) + (o1[0] * o1[0] + o1[1] * o1[1]) + (o1[2] * o1[2] + o1[3] * o1[3]);
;                 }
;                 if (ssq_off >= 0) { ss += __shfl_xor(ss, 16); ss += __shfl_xor(ss, 32); if (fq == 0) __hip_atomic_fetch_add(ssq + row, ss, __ATOMIC_RELAXED, __HIP_MEMORY_SCOPE_AGENT); }
.LBB0_461:
	s_or_b64 exec, exec, s[66:67]
	v_lshlrev_b32_e32 v112, 16, v148
	s_waitcnt lgkmcnt(0)
	v_and_b32_e32 v113, 0xffff0000, v148
	v_lshlrev_b32_e32 v114, 16, v149
	v_and_b32_e32 v115, 0xffff0000, v149
	v_lshlrev_b32_e32 v116, 16, v150
	v_and_b32_e32 v117, 0xffff0000, v150
	v_lshlrev_b32_e32 v118, 16, v151
	v_and_b32_e32 v119, 0xffff0000, v151
	v_lshlrev_b32_e32 v124, 16, v146
	v_and_b32_e32 v125, 0xffff0000, v146
	v_lshlrev_b32_e32 v126, 16, v147
	v_and_b32_e32 v127, 0xffff0000, v147
	v_pk_add_f32 v[110:111], v[110:111], v[114:115]
	v_pk_add_f32 v[108:109], v[108:109], v[112:113]
	v_pk_add_f32 v[112:113], v[106:107], v[118:119]
	v_pk_add_f32 v[114:115], v[104:105], v[116:117]
	v_pk_add_f32 v[116:117], v[98:99], v[126:127]
	v_pk_add_f32 v[118:119], v[96:97], v[124:125]
	v_mul_f32_e32 v97, v109, v109
	v_mul_f32_e32 v98, v111, v111
	v_fmac_f32_e32 v97, v108, v108
	v_fmac_f32_e32 v98, v110, v110
	v_lshlrev_b32_e32 v120, 16, v144
	v_and_b32_e32 v121, 0xffff0000, v144
	v_lshlrev_b32_e32 v122, 16, v145
	v_and_b32_e32 v123, 0xffff0000, v145
	v_add_f32_e32 v97, v97, v98
	v_mul_f32_e32 v98, v115, v115
	v_pk_add_f32 v[102:103], v[102:103], v[122:123]
	v_pk_add_f32 v[100:101], v[100:101], v[120:121]
	v_fmac_f32_e32 v98, v114, v114
	v_add_f32_e32 v97, v98, v97
	v_mul_f32_e32 v98, v101, v101
	v_mul_f32_e32 v99, v103, v103
	v_mul_f32_e32 v96, v113, v113
	v_fmac_f32_e32 v98, v100, v100
	v_fmac_f32_e32 v99, v102, v102
	v_fmac_f32_e32 v96, v112, v112
	v_add_f32_e32 v98, v98, v99
	v_mul_f32_e32 v99, v119, v119
	v_add_f32_e32 v96, v96, v97
	v_mul_f32_e32 v97, v117, v117
	v_fmac_f32_e32 v99, v118, v118
	v_fmac_f32_e32 v97, v116, v116
	v_add_f32_e32 v98, v99, v98
	v_add_f32_e32 v97, v97, v98
	v_add_f32_e32 v96, v96, v97
	ds_bpermute_b32 v97, v197, v96
	v_lshl_add_u64 v[144:145], s[58:59], 0, v[180:181]
	v_cvt_pk_bf16_f32 v104, v108, v109
	v_lshl_add_u64 v[108:109], v[164:165], 1, v[144:145]
	v_cvt_pk_bf16_f32 v105, v110, v111
	s_waitcnt lgkmcnt(0)
	v_add_f32_e32 v96, v96, v97
	ds_bpermute_b32 v97, v198, v96
	v_cvt_pk_bf16_f32 v106, v114, v115
	v_cvt_pk_bf16_f32 v107, v112, v113
	global_store_dwordx4 v[108:109], v[104:107], off sc1
	v_cvt_pk_bf16_f32 v98, v100, v101
	v_cvt_pk_bf16_f32 v99, v102, v103
	v_cvt_pk_bf16_f32 v100, v118, v119
	v_cvt_pk_bf16_f32 v101, v116, v117
	global_store_dwordx4 v[108:109], v[98:101], off offset:256 sc1
	s_and_saveexec_b64 s[66:67], vcc
	s_cbranch_execz .LBB0_463
	s_waitcnt lgkmcnt(0)
	v_add_f32_e32 v98, v96, v97
	v_lshl_add_u64 v[96:97], v[176:177], 2, s[56:57]
	global_atomic_add_f32 v[96:97], v98, off
.LBB0_463:
	s_or_b64 exec, exec, s[66:67]
	v_lshlrev_b32_e32 v96, 16, v140
	s_waitcnt lgkmcnt(0)
	v_and_b32_e32 v97, 0xffff0000, v140
	v_lshlrev_b32_e32 v98, 16, v141
	v_and_b32_e32 v99, 0xffff0000, v141
	v_lshlrev_b32_e32 v100, 16, v142
	v_and_b32_e32 v101, 0xffff0000, v142
	v_lshlrev_b32_e32 v102, 16, v143
	v_and_b32_e32 v103, 0xffff0000, v143
	v_lshlrev_b32_e32 v108, 16, v138
	v_and_b32_e32 v109, 0xffff0000, v138
	v_lshlrev_b32_e32 v110, 16, v139
	v_and_b32_e32 v111, 0xffff0000, v139
	v_pk_add_f32 v[94:95], v[94:95], v[98:99]
	v_pk_add_f32 v[92:93], v[92:93], v[96:97]
	v_pk_add_f32 v[96:97], v[90:91], v[102:103]
	v_pk_add_f32 v[98:99], v[88:89], v[100:101]
	v_pk_add_f32 v[100:101], v[82:83], v[110:111]
	v_pk_add_f32 v[102:103], v[80:81], v[108:109]
	v_mul_f32_e32 v81, v93, v93
	v_mul_f32_e32 v82, v95, v95
	v_fmac_f32_e32 v81, v92, v92
	v_fmac_f32_e32 v82, v94, v94
	v_lshlrev_b32_e32 v104, 16, v136
	v_and_b32_e32 v105, 0xffff0000, v136
	v_lshlrev_b32_e32 v106, 16, v137
	v_and_b32_e32 v107, 0xffff0000, v137
	v_add_f32_e32 v81, v81, v82
	v_mul_f32_e32 v82, v99, v99
	v_pk_add_f32 v[86:87], v[86:87], v[106:107]
	v_pk_add_f32 v[84:85], v[84:85], v[104:105]
	v_fmac_f32_e32 v82, v98, v98
	v_add_f32_e32 v81, v82, v81
	v_mul_f32_e32 v82, v85, v85
	v_mul_f32_e32 v83, v87, v87
	v_mul_f32_e32 v80, v97, v97
	v_fmac_f32_e32 v82, v84, v84
	v_fmac_f32_e32 v83, v86, v86
	v_fmac_f32_e32 v80, v96, v96
	v_add_f32_e32 v82, v82, v83
	v_mul_f32_e32 v83, v103, v103
	v_add_f32_e32 v80, v80, v81
	v_mul_f32_e32 v81, v101, v101
	v_fmac_f32_e32 v83, v102, v102
	v_fmac_f32_e32 v81, v100, v100
	v_add_f32_e32 v82, v83, v82
	v_add_f32_e32 v81, v81, v82
	v_add_f32_e32 v80, v80, v81
	ds_bpermute_b32 v81, v197, v80
	v_lshl_add_u64 v[112:113], s[58:59], 0, v[178:179]
	v_cvt_pk_bf16_f32 v88, v92, v93
	v_lshl_add_u64 v[92:93], v[164:165], 1, v[112:113]
	v_cvt_pk_bf16_f32 v89, v94, v95
	s_waitcnt lgkmcnt(0)
	v_add_f32_e32 v80, v80, v81
	ds_bpermute_b32 v81, v198, v80
	v_cvt_pk_bf16_f32 v90, v98, v99
	v_cvt_pk_bf16_f32 v91, v96, v97
	global_store_dwordx4 v[92:93], v[88:91], off sc1
	v_cvt_pk_bf16_f32 v82, v84, v85
	v_cvt_pk_bf16_f32 v83, v86, v87
	v_cvt_pk_bf16_f32 v84, v102, v103
	v_cvt_pk_bf16_f32 v85, v100, v101
	global_store_dwordx4 v[92:93], v[82:85], off offset:256 sc1
	s_and_saveexec_b64 s[66:67], vcc
	s_cbranch_execz .LBB0_465
	s_waitcnt lgkmcnt(0)
	v_add_f32_e32 v82, v80, v81
	v_lshl_add_u64 v[80:81], v[172:173], 2, s[56:57]
	global_atomic_add_f32 v[80:81], v82, off
; __device__ __forceinline__ unsigned cvt_pk(float lo, float hi) { unsigned r; asm("v_cvt_pk_bf16_f32 %0, %1, %2" : "=v"(r) : "v"(lo), "v"(hi)); return r; }
;     __device__ __forceinline__ void operator()(AccRef acc, const pg8::Unit& u, int wr, int wc, int, int) const {
;     ...
;                 v4u pw[4][2];
; #pragma unroll
;                 for (int m = 0; m < 4; ++m) { const int row = u.pm * 256 + ai * 128 + wr * 64 + m * 16 + fr;
; #pragma unroll
;                     for (int bj = 0; bj < 2; ++bj) pw[m][bj] = *(const v4u*)(RB + (size_t)row * DM + u.pn * 256 + bj * 128 + wc * 32 + 8 * fq); }
; #pragma unroll
;                 for (int m = 0; m < 4; ++m)
; #pragma unroll
;                     for (int bj = 0; bj < 2; ++bj) { const v4u w = pw[m][bj]; r0[m][bj] = (f32x4){bf_lo(w.x), bf_hi(w.x), bf_lo(w.y), bf_hi(w.y)}; r1[m][bj] = (f32x4){bf_lo(w.z), bf_hi(w.z), bf_lo(w.w), bf_hi(w.w)}; }
;             }
;             asm volatile("" ::: "memory");
; #pragma unroll
;             for (int m = 0; m < 4; ++m) {
;                 const int row = u.pm * 256 + ai * 128 + wr * 64 + m * 16 + fr;
;                 float ss = 0.f;
; #pragma unroll
;                 for (int bj = 0; bj < 2; ++bj) {
;                     const int c0 = u.pn * 256 + bj * 128 + wc * 32 + 8 * fq;
;                     const f32x4 o0 = r0[m][bj] + acc[ai][bj][m][0], o1 = r1[m][bj] + acc[ai][bj][m][1];
;                     v4u w; w.x = cvt_pk(o0[0], o0[1]); w.y = cvt_pk(o0[2], o0[3]); w.z = cvt_pk(o1[0], o1[1]); w.w = cvt_pk(o1[2], o1[3]);
;                     *(v4u*)(HB + (size_t)row * DM + c0) = w;
;                     ss += (o0[0] * o0[0] + o0[1] * o0[1]) + (o0[2] * o0[2] + o0[3] * o0[3]) + (o1[0] * o1[0] + o1[1] * o1[1]) + (o1[2] * o1[2] + o1[3] * o1[3]);
;                 }
;                 if (ssq_off >= 0) { ss += __shfl_xor(ss, 16); ss += __shfl_xor(ss, 32); if (fq == 0) __hip_atomic_fetch_add(ssq + row, ss, __ATOMIC_RELAXED, __HIP_MEMORY_SCOPE_AGENT); }
.LBB0_465:
	s_or_b64 exec, exec, s[66:67]
	v_lshlrev_b32_e32 v80, 16, v132
	s_waitcnt lgkmcnt(0)
	v_and_b32_e32 v81, 0xffff0000, v132
	v_lshlrev_b32_e32 v82, 16, v133
	v_and_b32_e32 v83, 0xffff0000, v133
	v_lshlrev_b32_e32 v84, 16, v134
	v_and_b32_e32 v85, 0xffff0000, v134
	v_lshlrev_b32_e32 v86, 16, v135
	v_and_b32_e32 v87, 0xffff0000, v135
	v_lshlrev_b32_e32 v92, 16, v130
	v_and_b32_e32 v93, 0xffff0000, v130
	v_lshlrev_b32_e32 v94, 16, v131
	v_and_b32_e32 v95, 0xffff0000, v131
	v_pk_add_f32 v[78:79], v[78:79], v[82:83]
	v_pk_add_f32 v[76:77], v[76:77], v[80:81]
	v_pk_add_f32 v[80:81], v[74:75], v[86:87]
	v_pk_add_f32 v[82:83], v[72:73], v[84:85]
	v_pk_add_f32 v[84:85], v[66:67], v[94:95]
	v_pk_add_f32 v[86:87], v[64:65], v[92:93]
	v_mul_f32_e32 v65, v77, v77
	v_mul_f32_e32 v66, v79, v79
	v_fmac_f32_e32 v65, v76, v76
	v_fmac_f32_e32 v66, v78, v78
	v_lshlrev_b32_e32 v88, 16, v128
	v_and_b32_e32 v89, 0xffff0000, v128
	v_lshlrev_b32_e32 v90, 16, v129
	v_and_b32_e32 v91, 0xffff0000, v129
	v_add_f32_e32 v65, v65, v66
	v_mul_f32_e32 v66, v83, v83
	v_pk_add_f32 v[70:71], v[70:71], v[90:91]
	v_pk_add_f32 v[68:69], v[68:69], v[88:89]
	v_fmac_f32_e32 v66, v82, v82
	v_add_f32_e32 v65, v66, v65
	v_mul_f32_e32 v66, v69, v69
	v_mul_f32_e32 v67, v71, v71
	v_mul_f32_e32 v64, v81, v81
	v_fmac_f32_e32 v66, v68, v68
	v_fmac_f32_e32 v67, v70, v70
	v_fmac_f32_e32 v64, v80, v80
	v_add_f32_e32 v66, v66, v67
	v_mul_f32_e32 v67, v87, v87
	v_add_f32_e32 v64, v64, v65
	v_mul_f32_e32 v65, v85, v85
	v_fmac_f32_e32 v67, v86, v86
	v_fmac_f32_e32 v65, v84, v84
	v_add_f32_e32 v66, v67, v66
	v_add_f32_e32 v65, v65, v66
	v_add_f32_e32 v64, v64, v65
	ds_bpermute_b32 v65, v197, v64
	v_lshl_add_u64 v[96:97], s[58:59], 0, v[174:175]
	v_cvt_pk_bf16_f32 v72, v76, v77
	v_lshl_add_u64 v[76:77], v[164:165], 1, v[96:97]
	v_cvt_pk_bf16_f32 v73, v78, v79
	s_waitcnt lgkmcnt(0)
	v_add_f32_e32 v64, v64, v65
	ds_bpermute_b32 v65, v198, v64
	v_cvt_pk_bf16_f32 v74, v82, v83
	v_cvt_pk_bf16_f32 v75, v80, v81
	global_store_dwordx4 v[76:77], v[72:75], off sc1
	v_cvt_pk_bf16_f32 v66, v68, v69
	v_cvt_pk_bf16_f32 v67, v70, v71
	v_cvt_pk_bf16_f32 v68, v86, v87
	v_cvt_pk_bf16_f32 v69, v84, v85
	global_store_dwordx4 v[76:77], v[66:69], off offset:256 sc1
	s_and_saveexec_b64 s[66:67], vcc
	s_cbranch_execz .LBB0_467
	s_waitcnt lgkmcnt(0)
	v_add_f32_e32 v66, v64, v65
	v_lshl_add_u64 v[64:65], v[170:171], 2, s[56:57]
	global_atomic_add_f32 v[64:65], v66, off
.LBB0_467:
	s_or_b64 exec, exec, s[66:67]
	v_add_u32_e32 v98, 0x80, v166
	v_ashrrev_i32_e32 v99, 31, v98
	v_lshlrev_b64 v[110:111], 11, v[98:99]
	s_waitcnt lgkmcnt(0)
	v_lshl_add_u64 v[64:65], v[168:169], 0, v[110:111]
	v_mov_b64_e32 v[102:103], v[212:213]
	v_mov_b64_e32 v[104:105], v[214:215]
	v_mov_b64_e32 v[106:107], v[216:217]
	v_mov_b64_e32 v[108:109], v[218:219]
	v_add_u32_e32 v94, 0x90, v166
	v_add_u32_e32 v92, 0xa0, v166
	v_add_u32_e32 v88, 0xb0, v166
	v_ashrrev_i32_e32 v95, 31, v94
	v_ashrrev_i32_e32 v93, 31, v92
	v_ashrrev_i32_e32 v89, 31, v88
	v_lshlrev_b64 v[100:101], 11, v[94:95]
	v_lshlrev_b64 v[96:97], 11, v[92:93]
	v_lshlrev_b64 v[90:91], 11, v[88:89]
	v_lshl_add_u64 v[64:65], v[168:169], 0, v[100:101]
	v_lshl_add_u64 v[66:67], v[168:169], 0, v[96:97]
	v_lshl_add_u64 v[112:113], v[168:169], 0, v[90:91]
	v_mov_b64_e32 v[84:85], v[220:221]
	v_mov_b64_e32 v[86:87], v[222:223]
	v_mov_b64_e32 v[80:81], v[224:225]
	v_mov_b64_e32 v[82:83], v[226:227]
	v_mov_b64_e32 v[76:77], v[228:229]
	v_mov_b64_e32 v[78:79], v[230:231]
	v_mov_b64_e32 v[72:73], v[232:233]
	v_mov_b64_e32 v[74:75], v[234:235]
	v_mov_b64_e32 v[68:69], v[236:237]
	v_mov_b64_e32 v[70:71], v[238:239]
	s_nop 0
	v_mov_b64_e32 v[64:65], v[240:241]
	v_mov_b64_e32 v[66:67], v[242:243]
	v_lshl_add_u64 v[110:111], s[58:59], 0, v[110:111]
	v_lshlrev_b32_e32 v112, 16, v102
	v_and_b32_e32 v113, 0xffff0000, v102
	v_lshlrev_b32_e32 v102, 16, v103
	v_and_b32_e32 v103, 0xffff0000, v103
	v_lshlrev_b32_e32 v116, 16, v106
	v_and_b32_e32 v117, 0xffff0000, v106
	v_lshlrev_b32_e32 v106, 16, v107
	v_and_b32_e32 v107, 0xffff0000, v107
	v_lshlrev_b32_e32 v114, 16, v104
	v_and_b32_e32 v115, 0xffff0000, v104
	v_lshlrev_b32_e32 v104, 16, v105
	v_and_b32_e32 v105, 0xffff0000, v105
	v_lshlrev_b32_e32 v118, 16, v108
	v_and_b32_e32 v119, 0xffff0000, v108
	v_lshlrev_b32_e32 v108, 16, v109
	v_and_b32_e32 v109, 0xffff0000, v109
	v_pk_add_f32 v[62:63], v[62:63], v[102:103]
	v_pk_add_f32 v[60:61], v[60:61], v[112:113]
	v_pk_add_f32 v[54:55], v[54:55], v[106:107]
	v_pk_add_f32 v[52:53], v[52:53], v[116:117]
	v_pk_add_f32 v[58:59], v[58:59], v[104:105]
	v_pk_add_f32 v[56:57], v[56:57], v[114:115]
	v_pk_add_f32 v[102:103], v[50:51], v[108:109]
	v_pk_add_f32 v[104:105], v[48:49], v[118:119]
	v_cvt_pk_bf16_f32 v48, v60, v61
	v_cvt_pk_bf16_f32 v49, v62, v63
	v_mul_f32_e32 v61, v61, v61
	v_mul_f32_e32 v63, v63, v63
	v_mul_f32_e32 v107, v53, v53
	v_mul_f32_e32 v108, v55, v55
	v_cvt_pk_bf16_f32 v50, v56, v57
	v_mul_f32_e32 v57, v57, v57
	v_mul_f32_e32 v109, v105, v105
	v_fmac_f32_e32 v61, v60, v60
	v_fmac_f32_e32 v63, v62, v62
	v_fmac_f32_e32 v107, v52, v52
	v_fmac_f32_e32 v108, v54, v54
	v_mul_f32_e32 v51, v59, v59
	v_mul_f32_e32 v106, v103, v103
	v_fmac_f32_e32 v57, v56, v56
	v_fmac_f32_e32 v109, v104, v104
	v_add_f32_e32 v56, v61, v63
	v_add_f32_e32 v60, v107, v108
	v_fmac_f32_e32 v51, v58, v58
	v_fmac_f32_e32 v106, v102, v102
	v_add_f32_e32 v56, v57, v56
	v_add_f32_e32 v57, v109, v60
	v_add_f32_e32 v51, v51, v56
	v_add_f32_e32 v56, v106, v57
	v_add_f32_e32 v60, v51, v56
	ds_bpermute_b32 v61, v197, v60
	v_lshl_add_u64 v[56:57], v[164:165], 1, v[110:111]
	v_cvt_pk_bf16_f32 v51, v58, v59
	global_store_dwordx4 v[56:57], v[48:51], off sc1
	s_waitcnt lgkmcnt(0)
	s_nop 0
	v_add_f32_e32 v48, v60, v61
	ds_bpermute_b32 v49, v198, v48
	v_cvt_pk_bf16_f32 v50, v52, v53
	v_cvt_pk_bf16_f32 v51, v54, v55
	v_cvt_pk_bf16_f32 v52, v104, v105
	v_cvt_pk_bf16_f32 v53, v102, v103
	global_store_dwordx4 v[56:57], v[50:53], off offset:256 sc1
	s_and_saveexec_b64 s[66:67], vcc
	s_cbranch_execz .LBB0_469
	s_waitcnt lgkmcnt(0)
	v_add_f32_e32 v50, v48, v49
	v_lshl_add_u64 v[48:49], v[98:99], 2, s[56:57]
	global_atomic_add_f32 v[48:49], v50, off
; __device__ __forceinline__ unsigned cvt_pk(float lo, float hi) { unsigned r; asm("v_cvt_pk_bf16_f32 %0, %1, %2" : "=v"(r) : "v"(lo), "v"(hi)); return r; }
;     __device__ __forceinline__ void operator()(AccRef acc, const pg8::Unit& u, int wr, int wc, int, int) const {
;     ...
;             for (int m = 0; m < 4; ++m) {
;                 const int row = u.pm * 256 + ai * 128 + wr * 64 + m * 16 + fr;
;                 float ss = 0.f;
; #pragma unroll
;                 for (int bj = 0; bj < 2; ++bj) {
;                     const int c0 = u.pn * 256 + bj * 128 + wc * 32 + 8 * fq;
;                     const f32x4 o0 = r0[m][bj] + acc[ai][bj][m][0], o1 = r1[m][bj] + acc[ai][bj][m][1];
;                     v4u w; w.x = cvt_pk(o0[0], o0[1]); w.y = cvt_pk(o0[2], o0[3]); w.z = cvt_pk(o1[0], o1[1]); w.w = cvt_pk(o1[2], o1[3]);
;                     *(v4u*)(HB + (size_t)row * DM + c0) = w;
;                     ss += (o0[0] * o0[0] + o0[1] * o0[1]) + (o0[2] * o0[2] + o0[3] * o0[3]) + (o1[0] * o1[0] + o1[1] * o1[1]) + (o1[2] * o1[2] + o1[3] * o1[3]);
;                 }
;                 if (ssq_off >= 0) { ss += __shfl_xor(ss, 16); ss += __shfl_xor(ss, 32); if (fq == 0) __hip_atomic_fetch_add(ssq + row, ss, __ATOMIC_RELAXED, __HIP_MEMORY_SCOPE_AGENT); }
.LBB0_469:
	s_or_b64 exec, exec, s[66:67]
	v_lshlrev_b32_e32 v48, 16, v84
	s_waitcnt lgkmcnt(0)
	v_and_b32_e32 v49, 0xffff0000, v84
	v_lshlrev_b32_e32 v50, 16, v85
	v_and_b32_e32 v51, 0xffff0000, v85
	v_lshlrev_b32_e32 v52, 16, v86
	v_and_b32_e32 v53, 0xffff0000, v86
	v_lshlrev_b32_e32 v54, 16, v87
	v_and_b32_e32 v55, 0xffff0000, v87
	v_lshlrev_b32_e32 v60, 16, v82
	v_and_b32_e32 v61, 0xffff0000, v82
	v_lshlrev_b32_e32 v62, 16, v83
	v_and_b32_e32 v63, 0xffff0000, v83
	v_pk_add_f32 v[46:47], v[46:47], v[50:51]
	v_pk_add_f32 v[44:45], v[44:45], v[48:49]
	v_pk_add_f32 v[48:49], v[42:43], v[54:55]
	v_pk_add_f32 v[50:51], v[40:41], v[52:53]
	v_pk_add_f32 v[52:53], v[34:35], v[62:63]
	v_pk_add_f32 v[54:55], v[32:33], v[60:61]
	v_mul_f32_e32 v33, v45, v45
	v_mul_f32_e32 v34, v47, v47
	v_fmac_f32_e32 v33, v44, v44
	v_fmac_f32_e32 v34, v46, v46
	v_lshlrev_b32_e32 v56, 16, v80
	v_and_b32_e32 v57, 0xffff0000, v80
	v_lshlrev_b32_e32 v58, 16, v81
	v_and_b32_e32 v59, 0xffff0000, v81
	v_add_f32_e32 v33, v33, v34
	v_mul_f32_e32 v34, v51, v51
	v_pk_add_f32 v[38:39], v[38:39], v[58:59]
	v_pk_add_f32 v[36:37], v[36:37], v[56:57]
	v_fmac_f32_e32 v34, v50, v50
	v_add_f32_e32 v33, v34, v33
	v_mul_f32_e32 v34, v37, v37
	v_mul_f32_e32 v35, v39, v39
	v_mul_f32_e32 v32, v49, v49
	v_fmac_f32_e32 v34, v36, v36
	v_fmac_f32_e32 v35, v38, v38
	v_fmac_f32_e32 v32, v48, v48
	v_add_f32_e32 v34, v34, v35
	v_mul_f32_e32 v35, v55, v55
	v_add_f32_e32 v32, v32, v33
	v_mul_f32_e32 v33, v53, v53
	v_fmac_f32_e32 v35, v54, v54
	v_fmac_f32_e32 v33, v52, v52
	v_add_f32_e32 v34, v35, v34
	v_add_f32_e32 v33, v33, v34
	v_add_f32_e32 v32, v32, v33
	ds_bpermute_b32 v33, v197, v32
	v_lshl_add_u64 v[80:81], s[58:59], 0, v[100:101]
	v_cvt_pk_bf16_f32 v40, v44, v45
	v_lshl_add_u64 v[44:45], v[164:165], 1, v[80:81]
	v_cvt_pk_bf16_f32 v41, v46, v47
	s_waitcnt lgkmcnt(0)
	v_add_f32_e32 v32, v32, v33
	ds_bpermute_b32 v33, v198, v32
	v_cvt_pk_bf16_f32 v42, v50, v51
	v_cvt_pk_bf16_f32 v43, v48, v49
	global_store_dwordx4 v[44:45], v[40:43], off sc1
	v_cvt_pk_bf16_f32 v34, v36, v37
	v_cvt_pk_bf16_f32 v35, v38, v39
	v_cvt_pk_bf16_f32 v36, v54, v55
	v_cvt_pk_bf16_f32 v37, v52, v53
	global_store_dwordx4 v[44:45], v[34:37], off offset:256 sc1
	s_and_saveexec_b64 s[66:67], vcc
	s_cbranch_execz .LBB0_471
	s_waitcnt lgkmcnt(0)
	v_add_f32_e32 v34, v32, v33
	v_lshl_add_u64 v[32:33], v[94:95], 2, s[56:57]
	global_atomic_add_f32 v[32:33], v34, off
; __device__ __forceinline__ unsigned cvt_pk(float lo, float hi) { unsigned r; asm("v_cvt_pk_bf16_f32 %0, %1, %2" : "=v"(r) : "v"(lo), "v"(hi)); return r; }
;     __device__ __forceinline__ void operator()(AccRef acc, const pg8::Unit& u, int wr, int wc, int, int) const {
;     ...
;             for (int m = 0; m < 4; ++m) {
;                 const int row = u.pm * 256 + ai * 128 + wr * 64 + m * 16 + fr;
;                 float ss = 0.f;
; #pragma unroll
;                 for (int bj = 0; bj < 2; ++bj) {
;                     const int c0 = u.pn * 256 + bj * 128 + wc * 32 + 8 * fq;
;                     const f32x4 o0 = r0[m][bj] + acc[ai][bj][m][0], o1 = r1[m][bj] + acc[ai][bj][m][1];
;                     v4u w; w.x = cvt_pk(o0[0], o0[1]); w.y = cvt_pk(o0[2], o0[3]); w.z = cvt_pk(o1[0], o1[1]); w.w = cvt_pk(o1[2], o1[3]);
;                     *(v4u*)(HB + (size_t)row * DM + c0) = w;
;                     ss += (o0[0] * o0[0] + o0[1] * o0[1]) + (o0[2] * o0[2] + o0[3] * o0[3]) + (o1[0] * o1[0] + o1[1] * o1[1]) + (o1[2] * o1[2] + o1[3] * o1[3]);
;                 }
;                 if (ssq_off >= 0) { ss += __shfl_xor(ss, 16); ss += __shfl_xor(ss, 32); if (fq == 0) __hip_atomic_fetch_add(ssq + row, ss, __ATOMIC_RELAXED, __HIP_MEMORY_SCOPE_AGENT); }
.LBB0_471:
	s_or_b64 exec, exec, s[66:67]
	v_lshlrev_b32_e32 v32, 16, v76
	s_waitcnt lgkmcnt(0)
	v_and_b32_e32 v33, 0xffff0000, v76
	v_lshlrev_b32_e32 v34, 16, v77
	v_and_b32_e32 v35, 0xffff0000, v77
	v_lshlrev_b32_e32 v36, 16, v78
	v_and_b32_e32 v37, 0xffff0000, v78
	v_lshlrev_b32_e32 v38, 16, v79
	v_and_b32_e32 v39, 0xffff0000, v79
	v_lshlrev_b32_e32 v44, 16, v74
	v_and_b32_e32 v45, 0xffff0000, v74
	v_lshlrev_b32_e32 v46, 16, v75
	v_and_b32_e32 v47, 0xffff0000, v75
	v_pk_add_f32 v[30:31], v[30:31], v[34:35]
	v_pk_add_f32 v[28:29], v[28:29], v[32:33]
	v_pk_add_f32 v[32:33], v[26:27], v[38:39]
	v_pk_add_f32 v[34:35], v[24:25], v[36:37]
	v_pk_add_f32 v[36:37], v[18:19], v[46:47]
	v_pk_add_f32 v[38:39], v[16:17], v[44:45]
	v_mul_f32_e32 v17, v29, v29
	v_mul_f32_e32 v18, v31, v31
	v_fmac_f32_e32 v17, v28, v28
	v_fmac_f32_e32 v18, v30, v30
	v_lshlrev_b32_e32 v40, 16, v72
	v_and_b32_e32 v41, 0xffff0000, v72
	v_lshlrev_b32_e32 v42, 16, v73
	v_and_b32_e32 v43, 0xffff0000, v73
	v_add_f32_e32 v17, v17, v18
	v_mul_f32_e32 v18, v35, v35
	v_pk_add_f32 v[22:23], v[22:23], v[42:43]
	v_pk_add_f32 v[20:21], v[20:21], v[40:41]
	v_fmac_f32_e32 v18, v34, v34
	v_add_f32_e32 v17, v18, v17
	v_mul_f32_e32 v18, v21, v21
	v_mul_f32_e32 v19, v23, v23
	v_mul_f32_e32 v16, v33, v33
	v_fmac_f32_e32 v18, v20, v20
	v_fmac_f32_e32 v19, v22, v22
	v_fmac_f32_e32 v16, v32, v32
	v_add_f32_e32 v18, v18, v19
	v_mul_f32_e32 v19, v39, v39
	v_add_f32_e32 v16, v16, v17
	v_mul_f32_e32 v17, v37, v37
	v_fmac_f32_e32 v19, v38, v38
	v_fmac_f32_e32 v17, v36, v36
	v_add_f32_e32 v18, v19, v18
	v_add_f32_e32 v17, v17, v18
	v_add_f32_e32 v16, v16, v17
	ds_bpermute_b32 v17, v197, v16
	v_lshl_add_u64 v[48:49], s[58:59], 0, v[96:97]
	v_cvt_pk_bf16_f32 v24, v28, v29
	v_lshl_add_u64 v[28:29], v[164:165], 1, v[48:49]
	v_cvt_pk_bf16_f32 v25, v30, v31
	s_waitcnt lgkmcnt(0)
	v_add_f32_e32 v16, v16, v17
	ds_bpermute_b32 v17, v198, v16
	v_cvt_pk_bf16_f32 v26, v34, v35
	v_cvt_pk_bf16_f32 v27, v32, v33
	global_store_dwordx4 v[28:29], v[24:27], off sc1
	v_cvt_pk_bf16_f32 v18, v20, v21
	v_cvt_pk_bf16_f32 v19, v22, v23
	v_cvt_pk_bf16_f32 v20, v38, v39
	v_cvt_pk_bf16_f32 v21, v36, v37
	global_store_dwordx4 v[28:29], v[18:21], off offset:256 sc1
	s_and_saveexec_b64 s[66:67], vcc
	s_cbranch_execz .LBB0_473
	s_waitcnt lgkmcnt(0)
	v_add_f32_e32 v18, v16, v17
	v_lshl_add_u64 v[16:17], v[92:93], 2, s[56:57]
	global_atomic_add_f32 v[16:17], v18, off
.LBB0_473:
	s_or_b64 exec, exec, s[66:67]
	v_lshlrev_b32_e32 v16, 16, v68
	s_waitcnt lgkmcnt(0)
	v_and_b32_e32 v17, 0xffff0000, v68
	v_lshlrev_b32_e32 v18, 16, v69
	v_and_b32_e32 v19, 0xffff0000, v69
	v_lshlrev_b32_e32 v20, 16, v70
	v_and_b32_e32 v21, 0xffff0000, v70
	v_lshlrev_b32_e32 v22, 16, v71
	v_and_b32_e32 v23, 0xffff0000, v71
	v_lshlrev_b32_e32 v28, 16, v66
	v_and_b32_e32 v29, 0xffff0000, v66
	v_lshlrev_b32_e32 v30, 16, v67
	v_and_b32_e32 v31, 0xffff0000, v67
	v_pk_add_f32 v[14:15], v[14:15], v[18:19]
	v_pk_add_f32 v[12:13], v[12:13], v[16:17]
	v_pk_add_f32 v[16:17], v[10:11], v[22:23]
	v_pk_add_f32 v[18:19], v[8:9], v[20:21]
	v_pk_add_f32 v[20:21], v[2:3], v[30:31]
	v_pk_add_f32 v[22:23], v[0:1], v[28:29]
	v_mul_f32_e32 v1, v13, v13
	v_mul_f32_e32 v2, v15, v15
	v_fmac_f32_e32 v1, v12, v12
	v_fmac_f32_e32 v2, v14, v14
	v_lshlrev_b32_e32 v24, 16, v64
	v_and_b32_e32 v25, 0xffff0000, v64
	v_lshlrev_b32_e32 v26, 16, v65
	v_and_b32_e32 v27, 0xffff0000, v65
	v_add_f32_e32 v1, v1, v2
	v_mul_f32_e32 v2, v19, v19
	v_pk_add_f32 v[6:7], v[6:7], v[26:27]
	v_pk_add_f32 v[4:5], v[4:5], v[24:25]
	v_fmac_f32_e32 v2, v18, v18
	v_add_f32_e32 v1, v2, v1
	v_mul_f32_e32 v2, v5, v5
	v_mul_f32_e32 v3, v7, v7
	v_mul_f32_e32 v0, v17, v17
	v_fmac_f32_e32 v2, v4, v4
	v_fmac_f32_e32 v3, v6, v6
	v_fmac_f32_e32 v0, v16, v16
	v_add_f32_e32 v2, v2, v3
	v_mul_f32_e32 v3, v23, v23
	v_add_f32_e32 v0, v0, v1
	v_mul_f32_e32 v1, v21, v21
	v_fmac_f32_e32 v3, v22, v22
	v_fmac_f32_e32 v1, v20, v20
	v_add_f32_e32 v2, v3, v2
	v_add_f32_e32 v1, v1, v2
	v_add_f32_e32 v0, v0, v1
	ds_bpermute_b32 v1, v197, v0
	v_lshl_add_u64 v[32:33], s[58:59], 0, v[90:91]
	v_cvt_pk_bf16_f32 v8, v12, v13
	v_lshl_add_u64 v[12:13], v[164:165], 1, v[32:33]
	v_cvt_pk_bf16_f32 v9, v14, v15
	s_waitcnt lgkmcnt(0)
	v_add_f32_e32 v0, v0, v1
	ds_bpermute_b32 v1, v198, v0
	v_cvt_pk_bf16_f32 v10, v18, v19
	v_cvt_pk_bf16_f32 v11, v16, v17
	global_store_dwordx4 v[12:13], v[8:11], off sc1
	v_cvt_pk_bf16_f32 v2, v4, v5
	v_cvt_pk_bf16_f32 v3, v6, v7
	v_cvt_pk_bf16_f32 v4, v22, v23
	v_cvt_pk_bf16_f32 v5, v20, v21
	global_store_dwordx4 v[12:13], v[2:5], off offset:256 sc1
	s_and_saveexec_b64 s[58:59], vcc
	s_cbranch_execz .LBB0_475
	s_waitcnt lgkmcnt(0)
	v_add_f32_e32 v2, v0, v1
	v_lshl_add_u64 v[0:1], v[88:89], 2, s[56:57]
	global_atomic_add_f32 v[0:1], v2, off

; __device__ __forceinline__ unsigned cvt_pk(float lo, float hi) { unsigned r; asm("v_cvt_pk_bf16_f32 %0, %1, %2" : "=v"(r) : "v"(lo), "v"(hi)); return r; }
;     __device__ __forceinline__ void operator()(AccRef acc, const pg8::Unit& u, int wr, int wc, int, int) const {
;     ...
;                 v4u pw[4][2];
; #pragma unroll
;                 for (int m = 0; m < 4; ++m) { const int row = u.pm * 256 + ai * 128 + wr * 64 + m * 16 + fr;
; #pragma unroll
;                     for (int bj = 0; bj < 2; ++bj) pw[m][bj] = *(const v4u*)(RB + (size_t)row * DM + u.pn * 256 + bj * 128 + wc * 32 + 8 * fq); }
; #pragma unroll
;                 for (int m = 0; m < 4; ++m)
; #pragma unroll
;                     for (int bj = 0; bj < 2; ++bj) { const v4u w = pw[m][bj]; r0[m][bj] = (f32x4){bf_lo(w.x), bf_hi(w.x), bf_lo(w.y), bf_hi(w.y)}; r1[m][bj] = (f32x4){bf_lo(w.z), bf_hi(w.z), bf_lo(w.w), bf_hi(w.w)}; }
;             }
;             asm volatile("" ::: "memory");
; #pragma unroll
;             for (int m = 0; m < 4; ++m) {
;                 const int row = u.pm * 256 + ai * 128 + wr * 64 + m * 16 + fr;
;                 float ss = 0.f;
; #pragma unroll
;                 for (int bj = 0; bj < 2; ++bj) {
;                     const int c0 = u.pn * 256 + bj * 128 + wc * 32 + 8 * fq;
;                     const f32x4 o0 = r0[m][bj] + acc[ai][bj][m][0], o1 = r1[m][bj] + acc[ai][bj][m][1];
;                     v4u w; w.x = cvt_pk(o0[0], o0[1]); w.y = cvt_pk(o0[2], o0[3]); w.z = cvt_pk(o1[0], o1[1]); w.w = cvt_pk(o1[2], o1[3]);
;                     *(v4u*)(HB + (size_t)row * DM + c0) = w;
;                     ss += (o0[0] * o0[0] + o0[1] * o0[1]) + (o0[2] * o0[2] + o0[3] * o0[3]) + (o1[0] * o1[0] + o1[1] * o1[1]) + (o1[2] * o1[2] + o1[3] * o1[3]);
;                 }
;                 if (ssq_off >= 0) { ss += __shfl_xor(ss, 16); ss += __shfl_xor(ss, 32); if (fq == 0) __hip_atomic_fetch_add(ssq + row, ss, __ATOMIC_RELAXED, __HIP_MEMORY_SCOPE_AGENT); }
.LBB0_1189:
	s_mov_b64 s[42:43], s[22:23]
	s_mov_b64 s[46:47], s[20:21]
	s_add_u32 s44, s46, 0x7800000
	s_addc_u32 s45, s47, 0
	s_add_u32 s42, s46, 0x64000
	s_addc_u32 s43, s47, 0
	s_lshl_b32 s15, s38, 8
	s_lshl_b32 s36, s36, 8
	v_mov_b32_e32 v187, v196
	s_add_i32 s15, s15, s35
	s_ashr_i32 s37, s36, 31
	s_nop 0
	v_and_or_b32 v166, v187, 15, s15
	s_or_b32 s15, s36, s28
	s_lshl_b64 s[36:37], s[36:37], 1
	s_add_u32 s17, s46, s36
	v_ashrrev_i32_e32 v128, 1, v187
	s_addc_u32 s37, s47, s37
	v_and_b32_e32 v164, -8, v128
	s_add_u32 s36, s17, s55
	s_addc_u32 s37, s37, 0
	v_ashrrev_i32_e32 v165, 31, v164
	v_lshl_add_u64 v[128:129], v[164:165], 1, s[36:37]
	v_ashrrev_i32_e32 v167, 31, v166
	v_lshl_add_u64 v[168:169], v[128:129], 0, s[12:13]
	v_lshlrev_b64 v[200:201], 11, v[166:167]
	v_lshl_add_u64 v[128:129], v[168:169], 0, v[200:201]
	s_mov_b64 s[56:57], 0x40000
	v_lshl_add_u64 v[244:245], v[128:129], 0, s[56:57]
	global_load_dwordx4 v[188:191], v[128:129], off
	global_load_dwordx4 v[192:195], v[128:129], off offset:256
	global_load_dwordx4 v[212:215], v[244:245], off
	global_load_dwordx4 v[216:219], v[244:245], off offset:256
	v_or_b32_e32 v176, 16, v166
	v_or_b32_e32 v174, 32, v166
	v_or_b32_e32 v170, 48, v166
	v_ashrrev_i32_e32 v177, 31, v176
	v_ashrrev_i32_e32 v175, 31, v174
	v_ashrrev_i32_e32 v171, 31, v170
	v_lshlrev_b64 v[180:181], 11, v[176:177]
	v_lshlrev_b64 v[178:179], 11, v[174:175]
	v_lshlrev_b64 v[172:173], 11, v[170:171]
	v_lshl_add_u64 v[128:129], v[168:169], 0, v[180:181]
	v_lshl_add_u64 v[130:131], v[168:169], 0, v[178:179]
	v_lshl_add_u64 v[202:203], v[168:169], 0, v[172:173]
	v_lshl_add_u64 v[244:245], v[128:129], 0, s[56:57]
	global_load_dwordx4 v[148:151], v[128:129], off
	global_load_dwordx4 v[144:147], v[128:129], off offset:256
	global_load_dwordx4 v[220:223], v[244:245], off
	global_load_dwordx4 v[224:227], v[244:245], off offset:256
	v_lshl_add_u64 v[244:245], v[130:131], 0, s[56:57]
	global_load_dwordx4 v[140:143], v[130:131], off
	global_load_dwordx4 v[136:139], v[130:131], off offset:256
	global_load_dwordx4 v[228:231], v[244:245], off
	global_load_dwordx4 v[232:235], v[244:245], off offset:256
	v_lshl_add_u64 v[244:245], v[202:203], 0, s[56:57]
	global_load_dwordx4 v[132:135], v[202:203], off
	s_nop 0
	global_load_dwordx4 v[128:131], v[202:203], off offset:256
	global_load_dwordx4 v[236:239], v[244:245], off
	global_load_dwordx4 v[240:243], v[244:245], off offset:256
	v_cmp_gt_u32_e32 vcc, 16, v187
	v_add_u32_e32 v164, s15, v164
	v_ashrrev_i32_e32 v165, 31, v164
	v_lshl_add_u64 v[200:201], s[44:45], 0, v[200:201]
	s_waitcnt vmcnt(0)
	v_lshlrev_b32_e32 v202, 16, v188
	v_and_b32_e32 v203, 0xffff0000, v188
	v_lshlrev_b32_e32 v188, 16, v189
	v_and_b32_e32 v189, 0xffff0000, v189
	v_lshlrev_b32_e32 v206, 16, v192
	v_and_b32_e32 v207, 0xffff0000, v192
	v_lshlrev_b32_e32 v192, 16, v193
	v_and_b32_e32 v193, 0xffff0000, v193
	v_lshlrev_b32_e32 v204, 16, v190
	v_and_b32_e32 v205, 0xffff0000, v190
	v_lshlrev_b32_e32 v190, 16, v191
	v_and_b32_e32 v191, 0xffff0000, v191
	v_lshlrev_b32_e32 v208, 16, v194
	v_and_b32_e32 v209, 0xffff0000, v194
	v_pk_add_f32 v[126:127], v[126:127], v[188:189]
	v_pk_add_f32 v[124:125], v[124:125], v[202:203]
	v_pk_add_f32 v[118:119], v[118:119], v[192:193]
	v_pk_add_f32 v[116:117], v[116:117], v[206:207]
	v_lshlrev_b32_e32 v194, 16, v195
	v_and_b32_e32 v195, 0xffff0000, v195
	v_pk_add_f32 v[122:123], v[122:123], v[190:191]
	v_pk_add_f32 v[120:121], v[120:121], v[204:205]
	v_pk_add_f32 v[190:191], v[112:113], v[208:209]
	v_cvt_pk_bf16_f32 v112, v124, v125
	v_cvt_pk_bf16_f32 v113, v126, v127
	v_mul_f32_e32 v125, v125, v125
	v_mul_f32_e32 v127, v127, v127
	v_mul_f32_e32 v192, v117, v117
	v_mul_f32_e32 v193, v119, v119
	v_pk_add_f32 v[188:189], v[114:115], v[194:195]
	v_cvt_pk_bf16_f32 v114, v120, v121
	v_mul_f32_e32 v121, v121, v121
	v_mul_f32_e32 v194, v191, v191
	v_fmac_f32_e32 v125, v124, v124
	v_fmac_f32_e32 v127, v126, v126
	v_fmac_f32_e32 v192, v116, v116
	v_fmac_f32_e32 v193, v118, v118
	v_mul_f32_e32 v115, v123, v123
	v_mul_f32_e32 v187, v189, v189
	v_fmac_f32_e32 v121, v120, v120
	v_fmac_f32_e32 v194, v190, v190
	v_add_f32_e32 v120, v125, v127
	v_add_f32_e32 v124, v192, v193
	v_fmac_f32_e32 v115, v122, v122
	v_fmac_f32_e32 v187, v188, v188
	v_add_f32_e32 v120, v121, v120
	v_add_f32_e32 v121, v194, v124
	v_add_f32_e32 v115, v115, v120
	v_add_f32_e32 v120, v187, v121
	v_add_f32_e32 v124, v115, v120
	ds_bpermute_b32 v125, v197, v124
	v_lshl_add_u64 v[120:121], v[164:165], 1, v[200:201]
	v_cvt_pk_bf16_f32 v115, v122, v123
	global_store_dwordx4 v[120:121], v[112:115], off sc1
	s_waitcnt lgkmcnt(0)
	s_nop 0
	v_add_f32_e32 v112, v124, v125
	ds_bpermute_b32 v113, v198, v112
	v_cvt_pk_bf16_f32 v114, v116, v117
	v_cvt_pk_bf16_f32 v115, v118, v119
	v_cvt_pk_bf16_f32 v116, v190, v191
	v_cvt_pk_bf16_f32 v117, v188, v189
	global_store_dwordx4 v[120:121], v[114:117], off offset:256 sc1
	s_and_saveexec_b64 s[36:37], vcc
	s_cbranch_execz .LBB0_1191
	s_waitcnt lgkmcnt(0)
	v_add_f32_e32 v114, v112, v113
	v_lshl_add_u64 v[112:113], v[166:167], 2, s[42:43]
	global_atomic_add_f32 v[112:113], v114, off
; __device__ __forceinline__ unsigned cvt_pk(float lo, float hi) { unsigned r; asm("v_cvt_pk_bf16_f32 %0, %1, %2" : "=v"(r) : "v"(lo), "v"(hi)); return r; }
;     __device__ __forceinline__ void operator()(AccRef acc, const pg8::Unit& u, int wr, int wc, int, int) const {
;     ...
;             for (int m = 0; m < 4; ++m) {
;                 const int row = u.pm * 256 + ai * 128 + wr * 64 + m * 16 + fr;
;                 float ss = 0.f;
; #pragma unroll
;                 for (int bj = 0; bj < 2; ++bj) {
;                     const int c0 = u.pn * 256 + bj * 128 + wc * 32 + 8 * fq;
;                     const f32x4 o0 = r0[m][bj] + acc[ai][bj][m][0], o1 = r1[m][bj] + acc[ai][bj][m][1];
;                     v4u w; w.x = cvt_pk(o0[0], o0[1]); w.y = cvt_pk(o0[2], o0[3]); w.z = cvt_pk(o1[0], o1[1]); w.w = cvt_pk(o1[2], o1[3]);
;                     *(v4u*)(HB + (size_t)row * DM + c0) = w;
;                     ss += (o0[0] * o0[0] + o0[1] * o0[1]) + (o0[2] * o0[2] + o0[3] * o0[3]) + (o1[0] * o1[0] + o1[1] * o1[1]) + (o1[2] * o1[2] + o1[3] * o1[3]);
;                 }
;                 if (ssq_off >= 0) { ss += __shfl_xor(ss, 16); ss += __shfl_xor(ss, 32); if (fq == 0) __hip_atomic_fetch_add(ssq + row, ss, __ATOMIC_RELAXED, __HIP_MEMORY_SCOPE_AGENT); }
.LBB0_1191:
	s_or_b64 exec, exec, s[36:37]
	v_lshlrev_b32_e32 v112, 16, v148
	s_waitcnt lgkmcnt(0)
	v_and_b32_e32 v113, 0xffff0000, v148
	v_lshlrev_b32_e32 v114, 16, v149
	v_and_b32_e32 v115, 0xffff0000, v149
	v_lshlrev_b32_e32 v116, 16, v150
	v_and_b32_e32 v117, 0xffff0000, v150
	v_lshlrev_b32_e32 v118, 16, v151
	v_and_b32_e32 v119, 0xffff0000, v151
	v_lshlrev_b32_e32 v124, 16, v146
	v_and_b32_e32 v125, 0xffff0000, v146
	v_lshlrev_b32_e32 v126, 16, v147
	v_and_b32_e32 v127, 0xffff0000, v147
	v_pk_add_f32 v[110:111], v[110:111], v[114:115]
	v_pk_add_f32 v[108:109], v[108:109], v[112:113]
	v_pk_add_f32 v[112:113], v[106:107], v[118:119]
	v_pk_add_f32 v[114:115], v[104:105], v[116:117]
	v_pk_add_f32 v[116:117], v[98:99], v[126:127]
	v_pk_add_f32 v[118:119], v[96:97], v[124:125]
	v_mul_f32_e32 v97, v109, v109
	v_mul_f32_e32 v98, v111, v111
	v_fmac_f32_e32 v97, v108, v108
	v_fmac_f32_e32 v98, v110, v110
	v_lshlrev_b32_e32 v120, 16, v144
	v_and_b32_e32 v121, 0xffff0000, v144
	v_lshlrev_b32_e32 v122, 16, v145
	v_and_b32_e32 v123, 0xffff0000, v145
	v_add_f32_e32 v97, v97, v98
	v_mul_f32_e32 v98, v115, v115
	v_pk_add_f32 v[102:103], v[102:103], v[122:123]
	v_pk_add_f32 v[100:101], v[100:101], v[120:121]
	v_fmac_f32_e32 v98, v114, v114
	v_add_f32_e32 v97, v98, v97
	v_mul_f32_e32 v98, v101, v101
	v_mul_f32_e32 v99, v103, v103
	v_mul_f32_e32 v96, v113, v113
	v_fmac_f32_e32 v98, v100, v100
	v_fmac_f32_e32 v99, v102, v102
	v_fmac_f32_e32 v96, v112, v112
	v_add_f32_e32 v98, v98, v99
	v_mul_f32_e32 v99, v119, v119
	v_add_f32_e32 v96, v96, v97
	v_mul_f32_e32 v97, v117, v117
	v_fmac_f32_e32 v99, v118, v118
	v_fmac_f32_e32 v97, v116, v116
	v_add_f32_e32 v98, v99, v98
	v_add_f32_e32 v97, v97, v98
	v_add_f32_e32 v96, v96, v97
	ds_bpermute_b32 v97, v197, v96
	v_lshl_add_u64 v[144:145], s[44:45], 0, v[180:181]
	v_cvt_pk_bf16_f32 v104, v108, v109
	v_lshl_add_u64 v[108:109], v[164:165], 1, v[144:145]
	v_cvt_pk_bf16_f32 v105, v110, v111
	s_waitcnt lgkmcnt(0)
	v_add_f32_e32 v96, v96, v97
	ds_bpermute_b32 v97, v198, v96
	v_cvt_pk_bf16_f32 v106, v114, v115
	v_cvt_pk_bf16_f32 v107, v112, v113
	global_store_dwordx4 v[108:109], v[104:107], off sc1
	v_cvt_pk_bf16_f32 v98, v100, v101
	v_cvt_pk_bf16_f32 v99, v102, v103
	v_cvt_pk_bf16_f32 v100, v118, v119
	v_cvt_pk_bf16_f32 v101, v116, v117
	global_store_dwordx4 v[108:109], v[98:101], off offset:256 sc1
	s_and_saveexec_b64 s[36:37], vcc
	s_cbranch_execz .LBB0_1193
	s_waitcnt lgkmcnt(0)
	v_add_f32_e32 v98, v96, v97
	v_lshl_add_u64 v[96:97], v[176:177], 2, s[42:43]
	global_atomic_add_f32 v[96:97], v98, off
.LBB0_1193:
	s_or_b64 exec, exec, s[36:37]
	v_lshlrev_b32_e32 v96, 16, v140
	s_waitcnt lgkmcnt(0)
	v_and_b32_e32 v97, 0xffff0000, v140
	v_lshlrev_b32_e32 v98, 16, v141
	v_and_b32_e32 v99, 0xffff0000, v141
	v_lshlrev_b32_e32 v100, 16, v142
	v_and_b32_e32 v101, 0xffff0000, v142
	v_lshlrev_b32_e32 v102, 16, v143
	v_and_b32_e32 v103, 0xffff0000, v143
	v_lshlrev_b32_e32 v108, 16, v138
	v_and_b32_e32 v109, 0xffff0000, v138
	v_lshlrev_b32_e32 v110, 16, v139
	v_and_b32_e32 v111, 0xffff0000, v139
	v_pk_add_f32 v[94:95], v[94:95], v[98:99]
	v_pk_add_f32 v[92:93], v[92:93], v[96:97]
	v_pk_add_f32 v[96:97], v[90:91], v[102:103]
	v_pk_add_f32 v[98:99], v[88:89], v[100:101]
	v_pk_add_f32 v[100:101], v[82:83], v[110:111]
	v_pk_add_f32 v[102:103], v[80:81], v[108:109]
	v_mul_f32_e32 v81, v93, v93
	v_mul_f32_e32 v82, v95, v95
	v_fmac_f32_e32 v81, v92, v92
	v_fmac_f32_e32 v82, v94, v94
	v_lshlrev_b32_e32 v104, 16, v136
	v_and_b32_e32 v105, 0xffff0000, v136
	v_lshlrev_b32_e32 v106, 16, v137
	v_and_b32_e32 v107, 0xffff0000, v137
	v_add_f32_e32 v81, v81, v82
	v_mul_f32_e32 v82, v99, v99
	v_pk_add_f32 v[86:87], v[86:87], v[106:107]
	v_pk_add_f32 v[84:85], v[84:85], v[104:105]
	v_fmac_f32_e32 v82, v98, v98
	v_add_f32_e32 v81, v82, v81
	v_mul_f32_e32 v82, v85, v85
	v_mul_f32_e32 v83, v87, v87
	v_mul_f32_e32 v80, v97, v97
	v_fmac_f32_e32 v82, v84, v84
	v_fmac_f32_e32 v83, v86, v86
	v_fmac_f32_e32 v80, v96, v96
	v_add_f32_e32 v82, v82, v83
	v_mul_f32_e32 v83, v103, v103
	v_add_f32_e32 v80, v80, v81
	v_mul_f32_e32 v81, v101, v101
	v_fmac_f32_e32 v83, v102, v102
	v_fmac_f32_e32 v81, v100, v100
	v_add_f32_e32 v82, v83, v82
	v_add_f32_e32 v81, v81, v82
	v_add_f32_e32 v80, v80, v81
	ds_bpermute_b32 v81, v197, v80
	v_lshl_add_u64 v[112:113], s[44:45], 0, v[178:179]
	v_cvt_pk_bf16_f32 v88, v92, v93
	v_lshl_add_u64 v[92:93], v[164:165], 1, v[112:113]
	v_cvt_pk_bf16_f32 v89, v94, v95
	s_waitcnt lgkmcnt(0)
	v_add_f32_e32 v80, v80, v81
	ds_bpermute_b32 v81, v198, v80
	v_cvt_pk_bf16_f32 v90, v98, v99
	v_cvt_pk_bf16_f32 v91, v96, v97
	global_store_dwordx4 v[92:93], v[88:91], off sc1
	v_cvt_pk_bf16_f32 v82, v84, v85
	v_cvt_pk_bf16_f32 v83, v86, v87
	v_cvt_pk_bf16_f32 v84, v102, v103
	v_cvt_pk_bf16_f32 v85, v100, v101
	global_store_dwordx4 v[92:93], v[82:85], off offset:256 sc1
	s_and_saveexec_b64 s[36:37], vcc
	s_cbranch_execz .LBB0_1195
	s_waitcnt lgkmcnt(0)
	v_add_f32_e32 v82, v80, v81
	v_lshl_add_u64 v[80:81], v[174:175], 2, s[42:43]
	global_atomic_add_f32 v[80:81], v82, off
; __device__ __forceinline__ unsigned cvt_pk(float lo, float hi) { unsigned r; asm("v_cvt_pk_bf16_f32 %0, %1, %2" : "=v"(r) : "v"(lo), "v"(hi)); return r; }
;     __device__ __forceinline__ void operator()(AccRef acc, const pg8::Unit& u, int wr, int wc, int, int) const {
;     ...
;                 v4u pw[4][2];
; #pragma unroll
;                 for (int m = 0; m < 4; ++m) { const int row = u.pm * 256 + ai * 128 + wr * 64 + m * 16 + fr;
; #pragma unroll
;                     for (int bj = 0; bj < 2; ++bj) pw[m][bj] = *(const v4u*)(RB + (size_t)row * DM + u.pn * 256 + bj * 128 + wc * 32 + 8 * fq); }
; #pragma unroll
;                 for (int m = 0; m < 4; ++m)
; #pragma unroll
;                     for (int bj = 0; bj < 2; ++bj) { const v4u w = pw[m][bj]; r0[m][bj] = (f32x4){bf_lo(w.x), bf_hi(w.x), bf_lo(w.y), bf_hi(w.y)}; r1[m][bj] = (f32x4){bf_lo(w.z), bf_hi(w.z), bf_lo(w.w), bf_hi(w.w)}; }
;             }
;             asm volatile("" ::: "memory");
; #pragma unroll
;             for (int m = 0; m < 4; ++m) {
;                 const int row = u.pm * 256 + ai * 128 + wr * 64 + m * 16 + fr;
;                 float ss = 0.f;
; #pragma unroll
;                 for (int bj = 0; bj < 2; ++bj) {
;                     const int c0 = u.pn * 256 + bj * 128 + wc * 32 + 8 * fq;
;                     const f32x4 o0 = r0[m][bj] + acc[ai][bj][m][0], o1 = r1[m][bj] + acc[ai][bj][m][1];
;                     v4u w; w.x = cvt_pk(o0[0], o0[1]); w.y = cvt_pk(o0[2], o0[3]); w.z = cvt_pk(o1[0], o1[1]); w.w = cvt_pk(o1[2], o1[3]);
;                     *(v4u*)(HB + (size_t)row * DM + c0) = w;
;                     ss += (o0[0] * o0[0] + o0[1] * o0[1]) + (o0[2] * o0[2] + o0[3] * o0[3]) + (o1[0] * o1[0] + o1[1] * o1[1]) + (o1[2] * o1[2] + o1[3] * o1[3]);
;                 }
;                 if (ssq_off >= 0) { ss += __shfl_xor(ss, 16); ss += __shfl_xor(ss, 32); if (fq == 0) __hip_atomic_fetch_add(ssq + row, ss, __ATOMIC_RELAXED, __HIP_MEMORY_SCOPE_AGENT); }
.LBB0_1195:
	s_or_b64 exec, exec, s[36:37]
	v_lshlrev_b32_e32 v80, 16, v132
	s_waitcnt lgkmcnt(0)
	v_and_b32_e32 v81, 0xffff0000, v132
	v_lshlrev_b32_e32 v82, 16, v133
	v_and_b32_e32 v83, 0xffff0000, v133
	v_lshlrev_b32_e32 v84, 16, v134
	v_and_b32_e32 v85, 0xffff0000, v134
	v_lshlrev_b32_e32 v86, 16, v135
	v_and_b32_e32 v87, 0xffff0000, v135
	v_lshlrev_b32_e32 v92, 16, v130
	v_and_b32_e32 v93, 0xffff0000, v130
	v_lshlrev_b32_e32 v94, 16, v131
	v_and_b32_e32 v95, 0xffff0000, v131
	v_pk_add_f32 v[78:79], v[78:79], v[82:83]
	v_pk_add_f32 v[76:77], v[76:77], v[80:81]
	v_pk_add_f32 v[80:81], v[74:75], v[86:87]
	v_pk_add_f32 v[82:83], v[72:73], v[84:85]
	v_pk_add_f32 v[84:85], v[66:67], v[94:95]
	v_pk_add_f32 v[86:87], v[64:65], v[92:93]
	v_mul_f32_e32 v65, v77, v77
	v_mul_f32_e32 v66, v79, v79
	v_fmac_f32_e32 v65, v76, v76
	v_fmac_f32_e32 v66, v78, v78
	v_lshlrev_b32_e32 v88, 16, v128
	v_and_b32_e32 v89, 0xffff0000, v128
	v_lshlrev_b32_e32 v90, 16, v129
	v_and_b32_e32 v91, 0xffff0000, v129
	v_add_f32_e32 v65, v65, v66
	v_mul_f32_e32 v66, v83, v83
	v_pk_add_f32 v[70:71], v[70:71], v[90:91]
	v_pk_add_f32 v[68:69], v[68:69], v[88:89]
	v_fmac_f32_e32 v66, v82, v82
	v_add_f32_e32 v65, v66, v65
	v_mul_f32_e32 v66, v69, v69
	v_mul_f32_e32 v67, v71, v71
	v_mul_f32_e32 v64, v81, v81
	v_fmac_f32_e32 v66, v68, v68
	v_fmac_f32_e32 v67, v70, v70
	v_fmac_f32_e32 v64, v80, v80
	v_add_f32_e32 v66, v66, v67
	v_mul_f32_e32 v67, v87, v87
	v_add_f32_e32 v64, v64, v65
	v_mul_f32_e32 v65, v85, v85
	v_fmac_f32_e32 v67, v86, v86
	v_fmac_f32_e32 v65, v84, v84
	v_add_f32_e32 v66, v67, v66
	v_add_f32_e32 v65, v65, v66
	v_add_f32_e32 v64, v64, v65
	ds_bpermute_b32 v65, v197, v64
	v_lshl_add_u64 v[96:97], s[44:45], 0, v[172:173]
	v_cvt_pk_bf16_f32 v72, v76, v77
	v_lshl_add_u64 v[76:77], v[164:165], 1, v[96:97]
	v_cvt_pk_bf16_f32 v73, v78, v79
	s_waitcnt lgkmcnt(0)
	v_add_f32_e32 v64, v64, v65
	ds_bpermute_b32 v65, v198, v64
	v_cvt_pk_bf16_f32 v74, v82, v83
	v_cvt_pk_bf16_f32 v75, v80, v81
	global_store_dwordx4 v[76:77], v[72:75], off sc1
	v_cvt_pk_bf16_f32 v66, v68, v69
	v_cvt_pk_bf16_f32 v67, v70, v71
	v_cvt_pk_bf16_f32 v68, v86, v87
	v_cvt_pk_bf16_f32 v69, v84, v85
	global_store_dwordx4 v[76:77], v[66:69], off offset:256 sc1
	s_and_saveexec_b64 s[36:37], vcc
	s_cbranch_execz .LBB0_1197
	s_waitcnt lgkmcnt(0)
	v_add_f32_e32 v66, v64, v65
	v_lshl_add_u64 v[64:65], v[170:171], 2, s[42:43]
	global_atomic_add_f32 v[64:65], v66, off
.LBB0_1197:
	s_or_b64 exec, exec, s[36:37]
	v_add_u32_e32 v98, 0x80, v166
	v_ashrrev_i32_e32 v99, 31, v98
	v_lshlrev_b64 v[110:111], 11, v[98:99]
	s_waitcnt lgkmcnt(0)
	v_lshl_add_u64 v[64:65], v[168:169], 0, v[110:111]
	v_mov_b64_e32 v[102:103], v[212:213]
	v_mov_b64_e32 v[104:105], v[214:215]
	v_mov_b64_e32 v[106:107], v[216:217]
	v_mov_b64_e32 v[108:109], v[218:219]
	v_add_u32_e32 v94, 0x90, v166
	v_add_u32_e32 v92, 0xa0, v166
	v_add_u32_e32 v88, 0xb0, v166
	v_ashrrev_i32_e32 v95, 31, v94
	v_ashrrev_i32_e32 v93, 31, v92
	v_ashrrev_i32_e32 v89, 31, v88
	v_lshlrev_b64 v[100:101], 11, v[94:95]
	v_lshlrev_b64 v[96:97], 11, v[92:93]
	v_lshlrev_b64 v[90:91], 11, v[88:89]
	v_lshl_add_u64 v[64:65], v[168:169], 0, v[100:101]
	v_lshl_add_u64 v[66:67], v[168:169], 0, v[96:97]
	v_lshl_add_u64 v[112:113], v[168:169], 0, v[90:91]
	v_mov_b64_e32 v[84:85], v[220:221]
	v_mov_b64_e32 v[86:87], v[222:223]
	v_mov_b64_e32 v[80:81], v[224:225]
	v_mov_b64_e32 v[82:83], v[226:227]
	v_mov_b64_e32 v[76:77], v[228:229]
	v_mov_b64_e32 v[78:79], v[230:231]
	v_mov_b64_e32 v[72:73], v[232:233]
	v_mov_b64_e32 v[74:75], v[234:235]
	v_mov_b64_e32 v[68:69], v[236:237]
	v_mov_b64_e32 v[70:71], v[238:239]
	s_nop 0
	v_mov_b64_e32 v[64:65], v[240:241]
	v_mov_b64_e32 v[66:67], v[242:243]
	v_lshl_add_u64 v[110:111], s[44:45], 0, v[110:111]
	v_lshlrev_b32_e32 v112, 16, v102
	v_and_b32_e32 v113, 0xffff0000, v102
	v_lshlrev_b32_e32 v102, 16, v103
	v_and_b32_e32 v103, 0xffff0000, v103
	v_lshlrev_b32_e32 v116, 16, v106
	v_and_b32_e32 v117, 0xffff0000, v106
	v_lshlrev_b32_e32 v106, 16, v107
	v_and_b32_e32 v107, 0xffff0000, v107
	v_lshlrev_b32_e32 v114, 16, v104
	v_and_b32_e32 v115, 0xffff0000, v104
	v_lshlrev_b32_e32 v104, 16, v105
	v_and_b32_e32 v105, 0xffff0000, v105
	v_lshlrev_b32_e32 v118, 16, v108
	v_and_b32_e32 v119, 0xffff0000, v108
	v_lshlrev_b32_e32 v108, 16, v109
	v_and_b32_e32 v109, 0xffff0000, v109
	v_pk_add_f32 v[62:63], v[62:63], v[102:103]
	v_pk_add_f32 v[60:61], v[60:61], v[112:113]
	v_pk_add_f32 v[54:55], v[54:55], v[106:107]
	v_pk_add_f32 v[52:53], v[52:53], v[116:117]
	v_pk_add_f32 v[58:59], v[58:59], v[104:105]
	v_pk_add_f32 v[56:57], v[56:57], v[114:115]
	v_pk_add_f32 v[102:103], v[50:51], v[108:109]
	v_pk_add_f32 v[104:105], v[48:49], v[118:119]
	v_cvt_pk_bf16_f32 v48, v60, v61
	v_cvt_pk_bf16_f32 v49, v62, v63
	v_mul_f32_e32 v61, v61, v61
	v_mul_f32_e32 v63, v63, v63
	v_mul_f32_e32 v107, v53, v53
	v_mul_f32_e32 v108, v55, v55
	v_cvt_pk_bf16_f32 v50, v56, v57
	v_mul_f32_e32 v57, v57, v57
	v_mul_f32_e32 v109, v105, v105
	v_fmac_f32_e32 v61, v60, v60
	v_fmac_f32_e32 v63, v62, v62
	v_fmac_f32_e32 v107, v52, v52
	v_fmac_f32_e32 v108, v54, v54
	v_mul_f32_e32 v51, v59, v59
	v_mul_f32_e32 v106, v103, v103
	v_fmac_f32_e32 v57, v56, v56
	v_fmac_f32_e32 v109, v104, v104
	v_add_f32_e32 v56, v61, v63
	v_add_f32_e32 v60, v107, v108
	v_fmac_f32_e32 v51, v58, v58
	v_fmac_f32_e32 v106, v102, v102
	v_add_f32_e32 v56, v57, v56
	v_add_f32_e32 v57, v109, v60
	v_add_f32_e32 v51, v51, v56
	v_add_f32_e32 v56, v106, v57
	v_add_f32_e32 v60, v51, v56
	ds_bpermute_b32 v61, v197, v60
	v_lshl_add_u64 v[56:57], v[164:165], 1, v[110:111]
	v_cvt_pk_bf16_f32 v51, v58, v59
	global_store_dwordx4 v[56:57], v[48:51], off sc1
	s_waitcnt lgkmcnt(0)
	s_nop 0
	v_add_f32_e32 v48, v60, v61
	ds_bpermute_b32 v49, v198, v48
	v_cvt_pk_bf16_f32 v50, v52, v53
	v_cvt_pk_bf16_f32 v51, v54, v55
	v_cvt_pk_bf16_f32 v52, v104, v105
	v_cvt_pk_bf16_f32 v53, v102, v103
	global_store_dwordx4 v[56:57], v[50:53], off offset:256 sc1
	s_and_saveexec_b64 s[36:37], vcc
	s_cbranch_execz .LBB0_1199
	s_waitcnt lgkmcnt(0)
	v_add_f32_e32 v50, v48, v49
	v_lshl_add_u64 v[48:49], v[98:99], 2, s[42:43]
	global_atomic_add_f32 v[48:49], v50, off
; __device__ __forceinline__ unsigned cvt_pk(float lo, float hi) { unsigned r; asm("v_cvt_pk_bf16_f32 %0, %1, %2" : "=v"(r) : "v"(lo), "v"(hi)); return r; }
;     __device__ __forceinline__ void operator()(AccRef acc, const pg8::Unit& u, int wr, int wc, int, int) const {
;     ...
;             for (int m = 0; m < 4; ++m) {
;                 const int row = u.pm * 256 + ai * 128 + wr * 64 + m * 16 + fr;
;                 float ss = 0.f;
; #pragma unroll
;                 for (int bj = 0; bj < 2; ++bj) {
;                     const int c0 = u.pn * 256 + bj * 128 + wc * 32 + 8 * fq;
;                     const f32x4 o0 = r0[m][bj] + acc[ai][bj][m][0], o1 = r1[m][bj] + acc[ai][bj][m][1];
;                     v4u w; w.x = cvt_pk(o0[0], o0[1]); w.y = cvt_pk(o0[2], o0[3]); w.z = cvt_pk(o1[0], o1[1]); w.w = cvt_pk(o1[2], o1[3]);
;                     *(v4u*)(HB + (size_t)row * DM + c0) = w;
;                     ss += (o0[0] * o0[0] + o0[1] * o0[1]) + (o0[2] * o0[2] + o0[3] * o0[3]) + (o1[0] * o1[0] + o1[1] * o1[1]) + (o1[2] * o1[2] + o1[3] * o1[3]);
;                 }
;                 if (ssq_off >= 0) { ss += __shfl_xor(ss, 16); ss += __shfl_xor(ss, 32); if (fq == 0) __hip_atomic_fetch_add(ssq + row, ss, __ATOMIC_RELAXED, __HIP_MEMORY_SCOPE_AGENT); }
.LBB0_1199:
	s_or_b64 exec, exec, s[36:37]
	v_lshlrev_b32_e32 v48, 16, v84
	s_waitcnt lgkmcnt(0)
	v_and_b32_e32 v49, 0xffff0000, v84
	v_lshlrev_b32_e32 v50, 16, v85
	v_and_b32_e32 v51, 0xffff0000, v85
	v_lshlrev_b32_e32 v52, 16, v86
	v_and_b32_e32 v53, 0xffff0000, v86
	v_lshlrev_b32_e32 v54, 16, v87
	v_and_b32_e32 v55, 0xffff0000, v87
	v_lshlrev_b32_e32 v60, 16, v82
	v_and_b32_e32 v61, 0xffff0000, v82
	v_lshlrev_b32_e32 v62, 16, v83
	v_and_b32_e32 v63, 0xffff0000, v83
	v_pk_add_f32 v[46:47], v[46:47], v[50:51]
	v_pk_add_f32 v[44:45], v[44:45], v[48:49]
	v_pk_add_f32 v[48:49], v[42:43], v[54:55]
	v_pk_add_f32 v[50:51], v[40:41], v[52:53]
	v_pk_add_f32 v[52:53], v[34:35], v[62:63]
	v_pk_add_f32 v[54:55], v[32:33], v[60:61]
	v_mul_f32_e32 v33, v45, v45
	v_mul_f32_e32 v34, v47, v47
	v_fmac_f32_e32 v33, v44, v44
	v_fmac_f32_e32 v34, v46, v46
	v_lshlrev_b32_e32 v56, 16, v80
	v_and_b32_e32 v57, 0xffff0000, v80
	v_lshlrev_b32_e32 v58, 16, v81
	v_and_b32_e32 v59, 0xffff0000, v81
	v_add_f32_e32 v33, v33, v34
	v_mul_f32_e32 v34, v51, v51
	v_pk_add_f32 v[38:39], v[38:39], v[58:59]
	v_pk_add_f32 v[36:37], v[36:37], v[56:57]
	v_fmac_f32_e32 v34, v50, v50
	v_add_f32_e32 v33, v34, v33
	v_mul_f32_e32 v34, v37, v37
	v_mul_f32_e32 v35, v39, v39
	v_mul_f32_e32 v32, v49, v49
	v_fmac_f32_e32 v34, v36, v36
	v_fmac_f32_e32 v35, v38, v38
	v_fmac_f32_e32 v32, v48, v48
	v_add_f32_e32 v34, v34, v35
	v_mul_f32_e32 v35, v55, v55
	v_add_f32_e32 v32, v32, v33
	v_mul_f32_e32 v33, v53, v53
	v_fmac_f32_e32 v35, v54, v54
	v_fmac_f32_e32 v33, v52, v52
	v_add_f32_e32 v34, v35, v34
	v_add_f32_e32 v33, v33, v34
	v_add_f32_e32 v32, v32, v33
	ds_bpermute_b32 v33, v197, v32
	v_lshl_add_u64 v[80:81], s[44:45], 0, v[100:101]
	v_cvt_pk_bf16_f32 v40, v44, v45
	v_lshl_add_u64 v[44:45], v[164:165], 1, v[80:81]
	v_cvt_pk_bf16_f32 v41, v46, v47
	s_waitcnt lgkmcnt(0)
	v_add_f32_e32 v32, v32, v33
	ds_bpermute_b32 v33, v198, v32
	v_cvt_pk_bf16_f32 v42, v50, v51
	v_cvt_pk_bf16_f32 v43, v48, v49
	global_store_dwordx4 v[44:45], v[40:43], off sc1
	v_cvt_pk_bf16_f32 v34, v36, v37
	v_cvt_pk_bf16_f32 v35, v38, v39
	v_cvt_pk_bf16_f32 v36, v54, v55
	v_cvt_pk_bf16_f32 v37, v52, v53
	global_store_dwordx4 v[44:45], v[34:37], off offset:256 sc1
	s_and_saveexec_b64 s[36:37], vcc
	s_cbranch_execz .LBB0_1201
	s_waitcnt lgkmcnt(0)
	v_add_f32_e32 v34, v32, v33
	v_lshl_add_u64 v[32:33], v[94:95], 2, s[42:43]
	global_atomic_add_f32 v[32:33], v34, off
; __device__ __forceinline__ unsigned cvt_pk(float lo, float hi) { unsigned r; asm("v_cvt_pk_bf16_f32 %0, %1, %2" : "=v"(r) : "v"(lo), "v"(hi)); return r; }
;     __device__ __forceinline__ void operator()(AccRef acc, const pg8::Unit& u, int wr, int wc, int, int) const {
;     ...
;             for (int m = 0; m < 4; ++m) {
;                 const int row = u.pm * 256 + ai * 128 + wr * 64 + m * 16 + fr;
;                 float ss = 0.f;
; #pragma unroll
;                 for (int bj = 0; bj < 2; ++bj) {
;                     const int c0 = u.pn * 256 + bj * 128 + wc * 32 + 8 * fq;
;                     const f32x4 o0 = r0[m][bj] + acc[ai][bj][m][0], o1 = r1[m][bj] + acc[ai][bj][m][1];
;                     v4u w; w.x = cvt_pk(o0[0], o0[1]); w.y = cvt_pk(o0[2], o0[3]); w.z = cvt_pk(o1[0], o1[1]); w.w = cvt_pk(o1[2], o1[3]);
;                     *(v4u*)(HB + (size_t)row * DM + c0) = w;
;                     ss += (o0[0] * o0[0] + o0[1] * o0[1]) + (o0[2] * o0[2] + o0[3] * o0[3]) + (o1[0] * o1[0] + o1[1] * o1[1]) + (o1[2] * o1[2] + o1[3] * o1[3]);
;                 }
;                 if (ssq_off >= 0) { ss += __shfl_xor(ss, 16); ss += __shfl_xor(ss, 32); if (fq == 0) __hip_atomic_fetch_add(ssq + row, ss, __ATOMIC_RELAXED, __HIP_MEMORY_SCOPE_AGENT); }
.LBB0_1201:
	s_or_b64 exec, exec, s[36:37]
	v_lshlrev_b32_e32 v32, 16, v76
	s_waitcnt lgkmcnt(0)
	v_and_b32_e32 v33, 0xffff0000, v76
	v_lshlrev_b32_e32 v34, 16, v77
	v_and_b32_e32 v35, 0xffff0000, v77
	v_lshlrev_b32_e32 v36, 16, v78
	v_and_b32_e32 v37, 0xffff0000, v78
	v_lshlrev_b32_e32 v38, 16, v79
	v_and_b32_e32 v39, 0xffff0000, v79
	v_lshlrev_b32_e32 v44, 16, v74
	v_and_b32_e32 v45, 0xffff0000, v74
	v_lshlrev_b32_e32 v46, 16, v75
	v_and_b32_e32 v47, 0xffff0000, v75
	v_pk_add_f32 v[30:31], v[30:31], v[34:35]
	v_pk_add_f32 v[28:29], v[28:29], v[32:33]
	v_pk_add_f32 v[32:33], v[26:27], v[38:39]
	v_pk_add_f32 v[34:35], v[24:25], v[36:37]
	v_pk_add_f32 v[36:37], v[18:19], v[46:47]
	v_pk_add_f32 v[38:39], v[16:17], v[44:45]
	v_mul_f32_e32 v17, v29, v29
	v_mul_f32_e32 v18, v31, v31
	v_fmac_f32_e32 v17, v28, v28
	v_fmac_f32_e32 v18, v30, v30
	v_lshlrev_b32_e32 v40, 16, v72
	v_and_b32_e32 v41, 0xffff0000, v72
	v_lshlrev_b32_e32 v42, 16, v73
	v_and_b32_e32 v43, 0xffff0000, v73
	v_add_f32_e32 v17, v17, v18
	v_mul_f32_e32 v18, v35, v35
	v_pk_add_f32 v[22:23], v[22:23], v[42:43]
	v_pk_add_f32 v[20:21], v[20:21], v[40:41]
	v_fmac_f32_e32 v18, v34, v34
	v_add_f32_e32 v17, v18, v17
	v_mul_f32_e32 v18, v21, v21
	v_mul_f32_e32 v19, v23, v23
	v_mul_f32_e32 v16, v33, v33
	v_fmac_f32_e32 v18, v20, v20
	v_fmac_f32_e32 v19, v22, v22
	v_fmac_f32_e32 v16, v32, v32
	v_add_f32_e32 v18, v18, v19
	v_mul_f32_e32 v19, v39, v39
	v_add_f32_e32 v16, v16, v17
	v_mul_f32_e32 v17, v37, v37
	v_fmac_f32_e32 v19, v38, v38
	v_fmac_f32_e32 v17, v36, v36
	v_add_f32_e32 v18, v19, v18
	v_add_f32_e32 v17, v17, v18
	v_add_f32_e32 v16, v16, v17
	ds_bpermute_b32 v17, v197, v16
	v_lshl_add_u64 v[48:49], s[44:45], 0, v[96:97]
	v_cvt_pk_bf16_f32 v24, v28, v29
	v_lshl_add_u64 v[28:29], v[164:165], 1, v[48:49]
	v_cvt_pk_bf16_f32 v25, v30, v31
	s_waitcnt lgkmcnt(0)
	v_add_f32_e32 v16, v16, v17
	ds_bpermute_b32 v17, v198, v16
	v_cvt_pk_bf16_f32 v26, v34, v35
	v_cvt_pk_bf16_f32 v27, v32, v33
	global_store_dwordx4 v[28:29], v[24:27], off sc1
	v_cvt_pk_bf16_f32 v18, v20, v21
	v_cvt_pk_bf16_f32 v19, v22, v23
	v_cvt_pk_bf16_f32 v20, v38, v39
	v_cvt_pk_bf16_f32 v21, v36, v37
	global_store_dwordx4 v[28:29], v[18:21], off offset:256 sc1
	s_and_saveexec_b64 s[36:37], vcc
	s_cbranch_execz .LBB0_1203
	s_waitcnt lgkmcnt(0)
	v_add_f32_e32 v18, v16, v17
	v_lshl_add_u64 v[16:17], v[92:93], 2, s[42:43]
	global_atomic_add_f32 v[16:17], v18, off
.LBB0_1203:
	s_or_b64 exec, exec, s[36:37]
	v_lshlrev_b32_e32 v16, 16, v68
	s_waitcnt lgkmcnt(0)
	v_and_b32_e32 v17, 0xffff0000, v68
	v_lshlrev_b32_e32 v18, 16, v69
	v_and_b32_e32 v19, 0xffff0000, v69
	v_lshlrev_b32_e32 v20, 16, v70
	v_and_b32_e32 v21, 0xffff0000, v70
	v_lshlrev_b32_e32 v22, 16, v71
	v_and_b32_e32 v23, 0xffff0000, v71
	v_lshlrev_b32_e32 v28, 16, v66
	v_and_b32_e32 v29, 0xffff0000, v66
	v_lshlrev_b32_e32 v30, 16, v67
	v_and_b32_e32 v31, 0xffff0000, v67
	v_pk_add_f32 v[14:15], v[14:15], v[18:19]
	v_pk_add_f32 v[12:13], v[12:13], v[16:17]
	v_pk_add_f32 v[16:17], v[10:11], v[22:23]
	v_pk_add_f32 v[18:19], v[8:9], v[20:21]
	v_pk_add_f32 v[20:21], v[2:3], v[30:31]
	v_pk_add_f32 v[22:23], v[0:1], v[28:29]
	v_mul_f32_e32 v1, v13, v13
	v_mul_f32_e32 v2, v15, v15
	v_fmac_f32_e32 v1, v12, v12
	v_fmac_f32_e32 v2, v14, v14
	v_lshlrev_b32_e32 v24, 16, v64
	v_and_b32_e32 v25, 0xffff0000, v64
	v_lshlrev_b32_e32 v26, 16, v65
	v_and_b32_e32 v27, 0xffff0000, v65
	v_add_f32_e32 v1, v1, v2
	v_mul_f32_e32 v2, v19, v19
	v_pk_add_f32 v[6:7], v[6:7], v[26:27]
	v_pk_add_f32 v[4:5], v[4:5], v[24:25]
	v_fmac_f32_e32 v2, v18, v18
	v_add_f32_e32 v1, v2, v1
	v_mul_f32_e32 v2, v5, v5
	v_mul_f32_e32 v3, v7, v7
	v_mul_f32_e32 v0, v17, v17
	v_fmac_f32_e32 v2, v4, v4
	v_fmac_f32_e32 v3, v6, v6
	v_fmac_f32_e32 v0, v16, v16
	v_add_f32_e32 v2, v2, v3
	v_mul_f32_e32 v3, v23, v23
	v_add_f32_e32 v0, v0, v1
	v_mul_f32_e32 v1, v21, v21
	v_fmac_f32_e32 v3, v22, v22
	v_fmac_f32_e32 v1, v20, v20
	v_add_f32_e32 v2, v3, v2
	v_add_f32_e32 v1, v1, v2
	v_add_f32_e32 v0, v0, v1
	ds_bpermute_b32 v1, v197, v0
	v_lshl_add_u64 v[32:33], s[44:45], 0, v[90:91]
	v_cvt_pk_bf16_f32 v8, v12, v13
	v_lshl_add_u64 v[12:13], v[164:165], 1, v[32:33]
	v_cvt_pk_bf16_f32 v9, v14, v15
	s_waitcnt lgkmcnt(0)
	v_add_f32_e32 v0, v0, v1
	ds_bpermute_b32 v1, v198, v0
	v_cvt_pk_bf16_f32 v10, v18, v19
	v_cvt_pk_bf16_f32 v11, v16, v17
	global_store_dwordx4 v[12:13], v[8:11], off sc1
	v_cvt_pk_bf16_f32 v2, v4, v5
	v_cvt_pk_bf16_f32 v3, v6, v7
	v_cvt_pk_bf16_f32 v4, v22, v23
	v_cvt_pk_bf16_f32 v5, v20, v21
	global_store_dwordx4 v[12:13], v[2:5], off offset:256 sc1
	s_and_saveexec_b64 s[36:37], vcc
	s_cbranch_execz .LBB0_1205
	s_waitcnt lgkmcnt(0)
	v_add_f32_e32 v2, v0, v1
	v_lshl_add_u64 v[0:1], v[88:89], 2, s[42:43]
	global_atomic_add_f32 v[0:1], v2, off
